# P3 W_in GEMM: skip the second MFMA group (all-zero padded weight columns) for the k_rope/pad N-tile
# baseline (speedup 1.0000x reference)
; #define PG8_STAGE(bufoff, gbase, voff) do { _Pragma("unroll") for (int _i = 0; _i < 2; ++_i) \
;         __builtin_amdgcn_global_load_lds((const unsigned*)((const char*)(gbase) + (BYTE_ELEMS ? _i * r##voff + (v##voff)[0] : (v##voff)[_i])), (PG8_LAS unsigned*)(lds + (bufoff) + ldsw + _i * 8192), 16, 0, 0); } while (0)
; #define PG8_LDA(dst, b, h) do { _Pragma("unroll") for (int m = 0; m < 4; ++m) _Pragma("unroll") for (int k = 0; k < 2; ++k) dst[m][k] = *(const PG8_LAS bf16x8*)(lds + PG8_SA(b, h) + aoff + m * 2048 + k * 1024); } while (0)
; #define PG8_LDB(dst, b, h) do { _Pragma("unroll") for (int n = 0; n < 2; ++n) _Pragma("unroll") for (int k = 0; k < 2; ++k) dst[n][k] = *(const PG8_LAS bf16x8*)(lds + PG8_SB(b, h) + boff + n * 2048 + k * 1024); } while (0)
; #define PG8_WAIT_V(n) asm volatile("s_waitcnt vmcnt(" #n ")" ::: "memory")
; #define PG8_WAIT_L(n) asm volatile("s_waitcnt lgkmcnt(" #n ")" ::: "memory")
; #define PG8_BAR __builtin_amdgcn_s_barrier()
; #define PG8_SCHED __builtin_amdgcn_sched_barrier(0)
;     ...
;             PG8_LDB(B0, 0, 0); PG8_LDB(B1, 0, 1); PG8_SCHED; PG8_LDA(At, 0, 0); PG8_STAGE(PG8_SA(1, 1), a1 + hstepA, offA);
;             PG8_WAIT_V(8); PG8_WAIT_L(0); PG8_BAR; PG8_MMA(0, 0, At, B0); PG8_MMA(0, 1, At, B1); PG8_BAR; PG8_SCHED;
;             PG8_LDA(At, 0, 1); PG8_STAGE(PG8_SB(0, 0), b2, offB); PG8_STAGE(PG8_SB(0, 1), b2 + hstepB, offB); PG8_STAGE(PG8_SA(0, 0), a2, offA);
;             PG8_WAIT_V(8); PG8_WAIT_L(0); PG8_BAR; PG8_MMA(1, 0, At, B0); PG8_MMA(1, 1, At, B1); PG8_BAR; PG8_SCHED;
.LBB0_476:
	ds_read_b128 v[144:147], v163
	ds_read_b128 v[148:151], v163 offset:1024
	ds_read_b128 v[152:155], v163 offset:2048
	ds_read_b128 v[156:159], v163 offset:3072
	ds_read_b128 v[168:171], v164
	ds_read_b128 v[172:175], v164 offset:1024
	ds_read_b128 v[176:179], v164 offset:2048
	ds_read_b128 v[180:183], v164 offset:3072
	s_add_u32 s4, s2, 0xfff80080
	s_addc_u32 s5, s3, -1
	s_cmp_eq_u32 s94, 28
	s_cselect_b32 s67, s1, s5
	s_cselect_b32 s66, s7, s4
	s_cselect_b32 s5, s57, s69
	s_cselect_b32 s4, s59, s68
	v_lshl_add_u64 v[160:161], s[2:3], 0, v[138:139]
	s_add_i32 m0, s71, 0xc000
	ds_read_b128 v[184:187], v165
	ds_read_b128 v[188:191], v165 offset:1024
	ds_read_b128 v[192:195], v165 offset:2048
	ds_read_b128 v[196:199], v165 offset:3072
	ds_read_b128 v[200:203], v165 offset:4096
	ds_read_b128 v[204:207], v165 offset:5120
	ds_read_b128 v[208:211], v165 offset:6144
	ds_read_b128 v[212:215], v165 offset:7168
	global_load_lds_dwordx4 v[160:161], off
	v_lshl_add_u64 v[160:161], s[2:3], 0, v[140:141]
	s_add_i32 m0, s71, 0xe000
	s_nop 0
	global_load_lds_dwordx4 v[160:161], off
	s_waitcnt vmcnt(8)
	s_waitcnt lgkmcnt(0)
	s_barrier
	s_setprio 1
	s_waitcnt lgkmcnt(0)
	v_mfma_f32_16x16x32_bf16 v[124:127], v[144:147], v[184:187], v[124:127]
	v_mfma_f32_16x16x32_bf16 v[120:123], v[152:155], v[184:187], v[120:123]
	v_mfma_f32_16x16x32_bf16 v[108:111], v[144:147], v[192:195], v[108:111]
	v_mfma_f32_16x16x32_bf16 v[104:107], v[152:155], v[192:195], v[104:107]
	v_mfma_f32_16x16x32_bf16 v[92:95], v[144:147], v[200:203], v[92:95]
	v_mfma_f32_16x16x32_bf16 v[88:91], v[152:155], v[200:203], v[88:91]
	v_mfma_f32_16x16x32_bf16 v[76:79], v[144:147], v[208:211], v[76:79]
	v_mfma_f32_16x16x32_bf16 v[72:75], v[152:155], v[208:211], v[72:75]
	v_mfma_f32_16x16x32_bf16 v[124:127], v[148:151], v[188:191], v[124:127]
	v_mfma_f32_16x16x32_bf16 v[120:123], v[156:159], v[188:191], v[120:123]
	v_mfma_f32_16x16x32_bf16 v[108:111], v[148:151], v[196:199], v[108:111]
	v_mfma_f32_16x16x32_bf16 v[104:107], v[156:159], v[196:199], v[104:107]
	v_mfma_f32_16x16x32_bf16 v[92:95], v[148:151], v[204:207], v[92:95]
	v_mfma_f32_16x16x32_bf16 v[88:91], v[156:159], v[204:207], v[88:91]
	v_mfma_f32_16x16x32_bf16 v[76:79], v[148:151], v[212:215], v[76:79]
	v_mfma_f32_16x16x32_bf16 v[72:75], v[156:159], v[212:215], v[72:75]
	s_setprio 0
	s_cmp_eq_u32 s6, 4
	s_cbranch_scc1 .Lzpad_skip_0
	s_setprio 1
	v_mfma_f32_16x16x32_bf16 v[116:119], v[168:171], v[184:187], v[116:119]
	v_mfma_f32_16x16x32_bf16 v[112:115], v[176:179], v[184:187], v[112:115]
	v_mfma_f32_16x16x32_bf16 v[100:103], v[168:171], v[192:195], v[100:103]
	v_mfma_f32_16x16x32_bf16 v[96:99], v[176:179], v[192:195], v[96:99]
	v_mfma_f32_16x16x32_bf16 v[84:87], v[168:171], v[200:203], v[84:87]
	v_mfma_f32_16x16x32_bf16 v[80:83], v[176:179], v[200:203], v[80:83]
	v_mfma_f32_16x16x32_bf16 v[68:71], v[168:171], v[208:211], v[68:71]
	v_mfma_f32_16x16x32_bf16 v[64:67], v[176:179], v[208:211], v[64:67]
	v_mfma_f32_16x16x32_bf16 v[116:119], v[172:175], v[188:191], v[116:119]
	v_mfma_f32_16x16x32_bf16 v[112:115], v[180:183], v[188:191], v[112:115]
	v_mfma_f32_16x16x32_bf16 v[100:103], v[172:175], v[196:199], v[100:103]
	v_mfma_f32_16x16x32_bf16 v[96:99], v[180:183], v[196:199], v[96:99]
	v_mfma_f32_16x16x32_bf16 v[84:87], v[172:175], v[204:207], v[84:87]
	v_mfma_f32_16x16x32_bf16 v[80:83], v[180:183], v[204:207], v[80:83]
	v_mfma_f32_16x16x32_bf16 v[68:71], v[172:175], v[212:215], v[68:71]
	v_mfma_f32_16x16x32_bf16 v[64:67], v[180:183], v[212:215], v[64:67]
.Lzpad_skip_0:
	s_setprio 0
	s_barrier
	s_add_i32 s95, s87, s70
	v_lshl_add_u64 v[160:161], s[4:5], 0, v[130:131]
	s_mov_b32 m0, s95
	ds_read_b128 v[184:187], v165 offset:16384
	ds_read_b128 v[188:191], v165 offset:17408
	ds_read_b128 v[192:195], v165 offset:18432
	ds_read_b128 v[196:199], v165 offset:19456
	ds_read_b128 v[200:203], v165 offset:20480
	ds_read_b128 v[204:207], v165 offset:21504
	ds_read_b128 v[208:211], v165 offset:22528
	ds_read_b128 v[212:215], v165 offset:23552
	global_load_lds_dwordx4 v[160:161], off
	s_add_i32 m0, s95, 0x2000
	s_add_u32 s96, s4, 0x80000
	v_lshl_add_u64 v[216:217], s[4:5], 0, v[134:135]
	s_addc_u32 s97, s5, 0
	s_add_i32 s95, s88, s70
	global_load_lds_dwordx4 v[216:217], off
	v_lshl_add_u64 v[218:219], s[96:97], 0, v[130:131]
	s_mov_b32 m0, s95
	v_lshl_add_u64 v[220:221], s[66:67], 0, v[132:133]
	global_load_lds_dwordx4 v[218:219], off
	v_lshl_add_u64 v[218:219], s[96:97], 0, v[134:135]
	s_add_i32 m0, s95, 0x2000
	s_nop 0
	global_load_lds_dwordx4 v[218:219], off
	v_lshl_add_u64 v[218:219], s[66:67], 0, v[128:129]
	s_mov_b32 m0, s71
	s_nop 0
	global_load_lds_dwordx4 v[218:219], off
	s_mov_b32 m0, s72
	s_nop 0
	global_load_lds_dwordx4 v[220:221], off
	s_waitcnt vmcnt(8)
	s_waitcnt lgkmcnt(0)
	s_barrier
	s_setprio 1
	s_waitcnt lgkmcnt(0)
	v_mfma_f32_16x16x32_bf16 v[60:63], v[144:147], v[184:187], v[60:63]
	v_mfma_f32_16x16x32_bf16 v[56:59], v[152:155], v[184:187], v[56:59]
	v_mfma_f32_16x16x32_bf16 v[44:47], v[144:147], v[192:195], v[44:47]
	v_mfma_f32_16x16x32_bf16 v[40:43], v[152:155], v[192:195], v[40:43]
	v_mfma_f32_16x16x32_bf16 v[28:31], v[144:147], v[200:203], v[28:31]
	v_mfma_f32_16x16x32_bf16 v[24:27], v[152:155], v[200:203], v[24:27]
	v_mfma_f32_16x16x32_bf16 v[12:15], v[144:147], v[208:211], v[12:15]
	v_mfma_f32_16x16x32_bf16 v[8:11], v[152:155], v[208:211], v[8:11]
	v_mfma_f32_16x16x32_bf16 v[60:63], v[148:151], v[188:191], v[60:63]
	v_mfma_f32_16x16x32_bf16 v[56:59], v[156:159], v[188:191], v[56:59]
	v_mfma_f32_16x16x32_bf16 v[44:47], v[148:151], v[196:199], v[44:47]
	v_mfma_f32_16x16x32_bf16 v[40:43], v[156:159], v[196:199], v[40:43]
	v_mfma_f32_16x16x32_bf16 v[28:31], v[148:151], v[204:207], v[28:31]
	v_mfma_f32_16x16x32_bf16 v[24:27], v[156:159], v[204:207], v[24:27]
	v_mfma_f32_16x16x32_bf16 v[12:15], v[148:151], v[212:215], v[12:15]
	v_mfma_f32_16x16x32_bf16 v[8:11], v[156:159], v[212:215], v[8:11]
	s_setprio 0
	s_cmp_eq_u32 s6, 4
	s_cbranch_scc1 .Lzpad_skip_1
; #define PG8_STAGE(bufoff, gbase, voff) do { _Pragma("unroll") for (int _i = 0; _i < 2; ++_i) \
;         __builtin_amdgcn_global_load_lds((const unsigned*)((const char*)(gbase) + (BYTE_ELEMS ? _i * r##voff + (v##voff)[0] : (v##voff)[_i])), (PG8_LAS unsigned*)(lds + (bufoff) + ldsw + _i * 8192), 16, 0, 0); } while (0)
; #define PG8_LDA(dst, b, h) do { _Pragma("unroll") for (int m = 0; m < 4; ++m) _Pragma("unroll") for (int k = 0; k < 2; ++k) dst[m][k] = *(const PG8_LAS bf16x8*)(lds + PG8_SA(b, h) + aoff + m * 2048 + k * 1024); } while (0)
; #define PG8_LDB(dst, b, h) do { _Pragma("unroll") for (int n = 0; n < 2; ++n) _Pragma("unroll") for (int k = 0; k < 2; ++k) dst[n][k] = *(const PG8_LAS bf16x8*)(lds + PG8_SB(b, h) + boff + n * 2048 + k * 1024); } while (0)
; #define PG8_WAIT_V(n) asm volatile("s_waitcnt vmcnt(" #n ")" ::: "memory")
; #define PG8_WAIT_L(n) asm volatile("s_waitcnt lgkmcnt(" #n ")" ::: "memory")
; #define PG8_BAR __builtin_amdgcn_s_barrier()
; #define PG8_SCHED __builtin_amdgcn_sched_barrier(0)
;     ...
;             PG8_WAIT_V(8); PG8_WAIT_L(0); PG8_BAR; PG8_MMA(1, 0, At, B0); PG8_MMA(1, 1, At, B1); PG8_BAR; PG8_SCHED;
;             PG8_LDB(B0, 1, 0); PG8_LDB(B1, 1, 1); PG8_SCHED; PG8_LDA(At, 1, 0); PG8_STAGE(PG8_SA(0, 1), a2 + hstepA, offA);
;             PG8_WAIT_V(8); PG8_WAIT_L(0); PG8_BAR; PG8_MMA(0, 0, At, B0); PG8_MMA(0, 1, At, B1); PG8_BAR; PG8_SCHED;
	s_setprio 1
	v_mfma_f32_16x16x32_bf16 v[52:55], v[168:171], v[184:187], v[52:55]
	v_mfma_f32_16x16x32_bf16 v[48:51], v[176:179], v[184:187], v[48:51]
	v_mfma_f32_16x16x32_bf16 v[36:39], v[168:171], v[192:195], v[36:39]
	v_mfma_f32_16x16x32_bf16 v[32:35], v[176:179], v[192:195], v[32:35]
	v_mfma_f32_16x16x32_bf16 v[20:23], v[168:171], v[200:203], v[20:23]
	v_mfma_f32_16x16x32_bf16 v[16:19], v[176:179], v[200:203], v[16:19]
	v_mfma_f32_16x16x32_bf16 v[4:7], v[168:171], v[208:211], v[4:7]
	v_mfma_f32_16x16x32_bf16 v[0:3], v[176:179], v[208:211], v[0:3]
	v_mfma_f32_16x16x32_bf16 v[52:55], v[172:175], v[188:191], v[52:55]
	v_mfma_f32_16x16x32_bf16 v[48:51], v[180:183], v[188:191], v[48:51]
	v_mfma_f32_16x16x32_bf16 v[36:39], v[172:175], v[196:199], v[36:39]
	v_mfma_f32_16x16x32_bf16 v[32:35], v[180:183], v[196:199], v[32:35]
	v_mfma_f32_16x16x32_bf16 v[20:23], v[172:175], v[204:207], v[20:23]
	v_mfma_f32_16x16x32_bf16 v[16:19], v[180:183], v[204:207], v[16:19]
	v_mfma_f32_16x16x32_bf16 v[4:7], v[172:175], v[212:215], v[4:7]
	v_mfma_f32_16x16x32_bf16 v[0:3], v[180:183], v[212:215], v[0:3]
.Lzpad_skip_1:
	s_setprio 0
	s_barrier
	s_add_i32 s95, 0, 0x18000
	v_add_u32_e32 v136, s95, v162
	s_add_i32 s96, 0, 0x1c000
	ds_read_b128 v[144:147], v136
	ds_read_b128 v[148:151], v136 offset:1024
	ds_read_b128 v[152:155], v136 offset:2048
	ds_read_b128 v[156:159], v136 offset:3072
	v_add_u32_e32 v136, s96, v162
	ds_read_b128 v[168:171], v136
	ds_read_b128 v[172:175], v136 offset:1024
	ds_read_b128 v[176:179], v136 offset:2048
	ds_read_b128 v[180:183], v136 offset:3072
	s_add_u32 s66, s66, 0x80000
	s_addc_u32 s67, s67, 0
	s_mov_b32 m0, s73
	v_lshl_add_u64 v[222:223], s[66:67], 0, v[128:129]
	ds_read_b128 v[184:187], v165 offset:32768
	ds_read_b128 v[188:191], v165 offset:33792
	ds_read_b128 v[192:195], v165 offset:34816
	ds_read_b128 v[196:199], v165 offset:35840
	ds_read_b128 v[200:203], v165 offset:36864
	ds_read_b128 v[204:207], v165 offset:37888
	ds_read_b128 v[208:211], v165 offset:38912
	ds_read_b128 v[212:215], v165 offset:39936
	global_load_lds_dwordx4 v[222:223], off
	v_lshl_add_u64 v[222:223], s[66:67], 0, v[132:133]
	s_mov_b32 m0, s76
	s_nop 0
	global_load_lds_dwordx4 v[222:223], off
	s_waitcnt vmcnt(8)
	s_waitcnt lgkmcnt(0)
	s_barrier
	s_setprio 1
	s_waitcnt lgkmcnt(0)
	v_mfma_f32_16x16x32_bf16 v[124:127], v[144:147], v[184:187], v[124:127]
	v_mfma_f32_16x16x32_bf16 v[120:123], v[152:155], v[184:187], v[120:123]
	v_mfma_f32_16x16x32_bf16 v[108:111], v[144:147], v[192:195], v[108:111]
	v_mfma_f32_16x16x32_bf16 v[104:107], v[152:155], v[192:195], v[104:107]
	v_mfma_f32_16x16x32_bf16 v[92:95], v[144:147], v[200:203], v[92:95]
	v_mfma_f32_16x16x32_bf16 v[88:91], v[152:155], v[200:203], v[88:91]
	v_mfma_f32_16x16x32_bf16 v[76:79], v[144:147], v[208:211], v[76:79]
	v_mfma_f32_16x16x32_bf16 v[72:75], v[152:155], v[208:211], v[72:75]
	v_mfma_f32_16x16x32_bf16 v[124:127], v[148:151], v[188:191], v[124:127]
	v_mfma_f32_16x16x32_bf16 v[120:123], v[156:159], v[188:191], v[120:123]
	v_mfma_f32_16x16x32_bf16 v[108:111], v[148:151], v[196:199], v[108:111]
	v_mfma_f32_16x16x32_bf16 v[104:107], v[156:159], v[196:199], v[104:107]
	v_mfma_f32_16x16x32_bf16 v[92:95], v[148:151], v[204:207], v[92:95]
	v_mfma_f32_16x16x32_bf16 v[88:91], v[156:159], v[204:207], v[88:91]
	v_mfma_f32_16x16x32_bf16 v[76:79], v[148:151], v[212:215], v[76:79]
	v_mfma_f32_16x16x32_bf16 v[72:75], v[156:159], v[212:215], v[72:75]
	s_setprio 0
	s_cmp_eq_u32 s6, 4
	s_cbranch_scc1 .Lzpad_skip_2
	s_setprio 1
	v_mfma_f32_16x16x32_bf16 v[116:119], v[168:171], v[184:187], v[116:119]
	v_mfma_f32_16x16x32_bf16 v[112:115], v[176:179], v[184:187], v[112:115]
	v_mfma_f32_16x16x32_bf16 v[100:103], v[168:171], v[192:195], v[100:103]
	v_mfma_f32_16x16x32_bf16 v[96:99], v[176:179], v[192:195], v[96:99]
	v_mfma_f32_16x16x32_bf16 v[84:87], v[168:171], v[200:203], v[84:87]
	v_mfma_f32_16x16x32_bf16 v[80:83], v[176:179], v[200:203], v[80:83]
	v_mfma_f32_16x16x32_bf16 v[68:71], v[168:171], v[208:211], v[68:71]
	v_mfma_f32_16x16x32_bf16 v[64:67], v[176:179], v[208:211], v[64:67]
	v_mfma_f32_16x16x32_bf16 v[116:119], v[172:175], v[188:191], v[116:119]
	v_mfma_f32_16x16x32_bf16 v[112:115], v[180:183], v[188:191], v[112:115]
	v_mfma_f32_16x16x32_bf16 v[100:103], v[172:175], v[196:199], v[100:103]
	v_mfma_f32_16x16x32_bf16 v[96:99], v[180:183], v[196:199], v[96:99]
	v_mfma_f32_16x16x32_bf16 v[84:87], v[172:175], v[204:207], v[84:87]
	v_mfma_f32_16x16x32_bf16 v[80:83], v[180:183], v[204:207], v[80:83]
	v_mfma_f32_16x16x32_bf16 v[68:71], v[172:175], v[212:215], v[68:71]
	v_mfma_f32_16x16x32_bf16 v[64:67], v[180:183], v[212:215], v[64:67]
; #define PG8_STAGE(bufoff, gbase, voff) do { _Pragma("unroll") for (int _i = 0; _i < 2; ++_i) \
;         __builtin_amdgcn_global_load_lds((const unsigned*)((const char*)(gbase) + (BYTE_ELEMS ? _i * r##voff + (v##voff)[0] : (v##voff)[_i])), (PG8_LAS unsigned*)(lds + (bufoff) + ldsw + _i * 8192), 16, 0, 0); } while (0)
; #define PG8_LDA(dst, b, h) do { _Pragma("unroll") for (int m = 0; m < 4; ++m) _Pragma("unroll") for (int k = 0; k < 2; ++k) dst[m][k] = *(const PG8_LAS bf16x8*)(lds + PG8_SA(b, h) + aoff + m * 2048 + k * 1024); } while (0)
; #define PG8_WAIT_V(n) asm volatile("s_waitcnt vmcnt(" #n ")" ::: "memory")
; #define PG8_WAIT_L(n) asm volatile("s_waitcnt lgkmcnt(" #n ")" ::: "memory")
; #define PG8_BAR __builtin_amdgcn_s_barrier()
; #define PG8_SCHED __builtin_amdgcn_sched_barrier(0)
;     ...
;             PG8_LDA(At, 1, 1); PG8_STAGE(PG8_SB(1, 0), b3, offB); PG8_STAGE(PG8_SB(1, 1), b3 + hstepB, offB); PG8_STAGE(PG8_SA(1, 0), a3, offA);
;             PG8_WAIT_V(8); PG8_WAIT_L(0); PG8_BAR; PG8_MMA(1, 0, At, B0); PG8_MMA(1, 1, At, B1); PG8_BAR; PG8_SCHED;
.Lzpad_skip_2:
	s_setprio 0
	s_barrier
	s_add_i32 s66, s95, s70
	v_lshl_add_u64 v[160:161], v[160:161], 0, s[50:51]
	s_mov_b32 m0, s66
	ds_read_b128 v[184:187], v165 offset:49152
	ds_read_b128 v[188:191], v165 offset:50176
	ds_read_b128 v[192:195], v165 offset:51200
	ds_read_b128 v[196:199], v165 offset:52224
	ds_read_b128 v[200:203], v165 offset:53248
	ds_read_b128 v[204:207], v165 offset:54272
	ds_read_b128 v[208:211], v165 offset:55296
	ds_read_b128 v[212:215], v165 offset:56320
	global_load_lds_dwordx4 v[160:161], off
	s_add_i32 m0, s66, 0x2000
	s_add_u32 s4, s4, 0x80080
	v_lshl_add_u64 v[160:161], v[216:217], 0, s[50:51]
	s_addc_u32 s5, s5, 0
	s_add_i32 s66, s96, s70
	global_load_lds_dwordx4 v[160:161], off
	v_lshl_add_u64 v[160:161], s[4:5], 0, v[130:131]
	s_mov_b32 m0, s66
	s_nop 0
	global_load_lds_dwordx4 v[160:161], off
	v_lshl_add_u64 v[160:161], s[4:5], 0, v[134:135]
	s_add_i32 m0, s66, 0x2000
	s_nop 0
	global_load_lds_dwordx4 v[160:161], off
	v_lshl_add_u64 v[160:161], v[218:219], 0, s[50:51]
	s_mov_b32 m0, s82
	s_nop 0
	global_load_lds_dwordx4 v[160:161], off
	v_lshl_add_u64 v[160:161], v[220:221], 0, s[50:51]
	s_mov_b32 m0, s83
	s_nop 0
	global_load_lds_dwordx4 v[160:161], off
	s_waitcnt vmcnt(8)
	s_waitcnt lgkmcnt(0)
	s_barrier
	s_setprio 1
	s_waitcnt lgkmcnt(0)
	v_mfma_f32_16x16x32_bf16 v[60:63], v[144:147], v[184:187], v[60:63]
	v_mfma_f32_16x16x32_bf16 v[56:59], v[152:155], v[184:187], v[56:59]
	v_mfma_f32_16x16x32_bf16 v[44:47], v[144:147], v[192:195], v[44:47]
	v_mfma_f32_16x16x32_bf16 v[40:43], v[152:155], v[192:195], v[40:43]
	v_mfma_f32_16x16x32_bf16 v[28:31], v[144:147], v[200:203], v[28:31]
	v_mfma_f32_16x16x32_bf16 v[24:27], v[152:155], v[200:203], v[24:27]
	v_mfma_f32_16x16x32_bf16 v[12:15], v[144:147], v[208:211], v[12:15]
	v_mfma_f32_16x16x32_bf16 v[8:11], v[152:155], v[208:211], v[8:11]
	v_mfma_f32_16x16x32_bf16 v[60:63], v[148:151], v[188:191], v[60:63]
	v_mfma_f32_16x16x32_bf16 v[56:59], v[156:159], v[188:191], v[56:59]
	v_mfma_f32_16x16x32_bf16 v[44:47], v[148:151], v[196:199], v[44:47]
	v_mfma_f32_16x16x32_bf16 v[40:43], v[156:159], v[196:199], v[40:43]
	v_mfma_f32_16x16x32_bf16 v[28:31], v[148:151], v[204:207], v[28:31]
	v_mfma_f32_16x16x32_bf16 v[24:27], v[156:159], v[204:207], v[24:27]
	v_mfma_f32_16x16x32_bf16 v[12:15], v[148:151], v[212:215], v[12:15]
	v_mfma_f32_16x16x32_bf16 v[8:11], v[156:159], v[212:215], v[8:11]
	s_setprio 0
	s_cmp_eq_u32 s6, 4
	s_cbranch_scc1 .Lzpad_skip_3
	s_setprio 1
	v_mfma_f32_16x16x32_bf16 v[52:55], v[168:171], v[184:187], v[52:55]
	v_mfma_f32_16x16x32_bf16 v[48:51], v[176:179], v[184:187], v[48:51]
	v_mfma_f32_16x16x32_bf16 v[36:39], v[168:171], v[192:195], v[36:39]
	v_mfma_f32_16x16x32_bf16 v[32:35], v[176:179], v[192:195], v[32:35]
	v_mfma_f32_16x16x32_bf16 v[20:23], v[168:171], v[200:203], v[20:23]
	v_mfma_f32_16x16x32_bf16 v[16:19], v[176:179], v[200:203], v[16:19]
	v_mfma_f32_16x16x32_bf16 v[4:7], v[168:171], v[208:211], v[4:7]
	v_mfma_f32_16x16x32_bf16 v[0:3], v[176:179], v[208:211], v[0:3]
	v_mfma_f32_16x16x32_bf16 v[52:55], v[172:175], v[188:191], v[52:55]
	v_mfma_f32_16x16x32_bf16 v[48:51], v[180:183], v[188:191], v[48:51]
	v_mfma_f32_16x16x32_bf16 v[36:39], v[172:175], v[196:199], v[36:39]
	v_mfma_f32_16x16x32_bf16 v[32:35], v[180:183], v[196:199], v[32:35]
	v_mfma_f32_16x16x32_bf16 v[20:23], v[172:175], v[204:207], v[20:23]
	v_mfma_f32_16x16x32_bf16 v[16:19], v[180:183], v[204:207], v[16:19]
	v_mfma_f32_16x16x32_bf16 v[4:7], v[172:175], v[212:215], v[4:7]
	v_mfma_f32_16x16x32_bf16 v[0:3], v[180:183], v[212:215], v[0:3]
.Lzpad_skip_3:
	s_setprio 0
	s_barrier
	s_add_i32 s94, s94, 2
	s_add_u32 s2, s2, 0x100
	s_addc_u32 s3, s3, 0
	s_add_u32 s68, s68, 0x100
	s_addc_u32 s69, s69, 0
	s_cmp_gt_u32 s94, 29
	s_cbranch_scc0 .LBB0_476
	s_and_b64 vcc, exec, s[52:53]
	s_cbranch_vccz .LBB0_479
	s_barrier
